# RG-LRU item prologue: 64 gate-weight loads issued 32 at a time with one wait (was 2 loads per vmcnt(0): 32 serial round trips per item)
# speedup vs baseline: 1.0051x; 1.0051x over previous
; __device__ __forceinline__ unsigned cvt_pk_bf16(float lo, float hi) { unsigned r; asm volatile("v_cvt_pk_bf16_f32 %0, %1, %2" : "=v"(r) : "v"(lo), "v"(hi)); return r; }
; __device__ __forceinline__ int ltid() { int t = threadIdx.x; asm volatile("" : "+v"(t)); return t; }
; __device__ __forceinline__ void lru_item(const Args& a, int l, int item, LAS unsigned char* lds) {
;     const int tid = ltid(), lane = tid & 63, wave = __builtin_amdgcn_readfirstlane(tid >> 6), fr = lane & 15, fq = lane >> 4;
;     int s, rem;
;     if (item < 64) { s = 16 + (item >> 4); rem = item & 15; } else { s = (item - 64) >> 4; rem = (item - 64) & 15; }
;     const int hd = rem >> 1, dir = rem & 1, L = seq_len(s);
;     const bf16_t* proj = (const bf16_t*)(a.ws + WS_BIG);
;     bf16_t* hfb = (bf16_t*)(a.ws + WS_BIG + BIG_HFB);
;     const size_t pbase = (size_t)(l * 2 + dir);
;     bf16x8 wfa[4], wfx[4];
;     {
;         const float* wa = a.in[15] + (pbase * 8 + hd) * 128 * 128; const float* wx = a.in[17] + (pbase * 8 + hd) * 128 * 128;
;         const int n = 16 * wave + fr;
; #pragma unroll
;         for (int ks = 0; ks < 4; ++ks) {
;             unsigned pa[4], px[4];
; #pragma unroll
;             for (int e = 0; e < 4; ++e) { const int k = 32 * ks + 8 * fq + 2 * e;
;                 pa[e] = cvt_pk_bf16(wa[k * 128 + n], wa[(k + 1) * 128 + n]); px[e] = cvt_pk_bf16(wx[k * 128 + n], wx[(k + 1) * 128 + n]); }
.LBB0_195:
	v_readlane_b32 s0, v251, 1
	s_ashr_i32 s0, s20, 4
	s_sub_i32 s1, s20, 64
	s_add_i32 s0, s0, 16
	s_lshr_b32 s1, s1, 4
	s_cmp_lt_i32 s20, 64
	s_cselect_b32 s4, s0, s1
	s_and_b32 s5, s20, 1
	s_or_b32 s0, s5, s31
	s_bfe_u32 s7, s20, 0x30001
	s_ashr_i32 s1, s0, 31
	s_lshl_b64 s[2:3], s[0:1], 19
	s_lshl_b32 s8, s7, 16
	v_readlane_b32 s52, v254, 23
	s_or_b32 s2, s2, s8
	v_readlane_b32 s53, v254, 24
	v_readlane_b32 s54, v254, 25
	v_readlane_b32 s55, v254, 26
	v_readlane_b32 s66, v254, 37
	s_mov_b32 s10, s50
	v_readlane_b32 s67, v254, 38
	s_add_u32 s12, s66, s2
	v_readlane_b32 s40, v254, 47
	v_mov_b32_e32 v1, v155
	s_addc_u32 s13, s67, s3
	v_readlane_b32 s42, v254, 49
	v_readlane_b32 s43, v254, 50
	v_readfirstlane_b32 s6, v1
	s_add_u32 s2, s42, s2
	v_bfe_u32 v124, v1, 4, 2
	s_addc_u32 s3, s43, s3
	s_ashr_i32 s6, s6, 2
	v_bfi_b32 v2, -16, s6, v1
	v_lshlrev_b32_e32 v16, 10, v124
	v_add_u32_e32 v34, v2, v16
	v_ashrrev_i32_e32 v35, 31, v34
	v_lshlrev_b64 v[4:5], 2, v[34:35]
	v_lshl_add_u64 v[12:13], s[12:13], 0, v[4:5]
	global_load_dword v130, v[12:13], off offset:512
	global_load_dword v131, v[12:13], off
	v_lshl_add_u64 v[14:15], s[2:3], 0, v[4:5]
	v_mov_b32_e32 v7, v0
	s_lshl_b32 s6, s7, 7
	v_readlane_b32 s62, v254, 33
	s_lshl_b64 s[8:9], s[0:1], 14
	v_readlane_b32 s63, v254, 34
	v_mov_b32_e32 v57, v0
	v_readlane_b32 s64, v254, 35
	v_readlane_b32 s65, v254, 36
	v_readlane_b32 s41, v254, 48
	v_readlane_b32 s44, v254, 51
	v_readlane_b32 s45, v254, 52
	v_readlane_b32 s46, v254, 53
	v_readlane_b32 s47, v254, 54
	v_bfe_u32 v127, v1, 4, 4
	v_readlane_b32 s56, v254, 27
	v_readlane_b32 s57, v254, 28
	v_readlane_b32 s58, v254, 29
	v_readlane_b32 s59, v254, 30
	v_readlane_b32 s60, v254, 31
	v_readlane_b32 s61, v254, 32
	v_readlane_b32 s48, v254, 55
	v_readlane_b32 s49, v254, 56
	v_readlane_b32 s50, v254, 57
	v_readlane_b32 s51, v254, 58
	v_readlane_b32 s52, v254, 59
	v_readlane_b32 s53, v254, 60
	v_readlane_b32 s54, v254, 61
	v_readlane_b32 s55, v254, 62
	global_load_dword v132, v[14:15], off offset:512
	global_load_dword v133, v[14:15], off
	v_or_b32_e32 v6, 0x100, v16
	v_ashrrev_i32_e32 v3, 31, v2
	v_lshl_add_u64 v[6:7], v[2:3], 0, v[6:7]
	v_lshlrev_b64 v[6:7], 2, v[6:7]
	v_lshl_add_u64 v[10:11], s[12:13], 0, v[6:7]
	v_lshl_add_u64 v[6:7], s[2:3], 0, v[6:7]
	global_load_dword v134, v[12:13], off offset:1024
	global_load_dword v135, v[10:11], off offset:512
	global_load_dword v136, v[14:15], off offset:1024
	global_load_dword v137, v[6:7], off offset:512
	v_mov_b32_e32 v7, v0
	v_or_b32_e32 v6, 0x200, v16
	v_lshl_add_u64 v[6:7], v[2:3], 0, v[6:7]
	v_lshlrev_b64 v[6:7], 2, v[6:7]
	v_lshl_add_u64 v[10:11], s[12:13], 0, v[6:7]
	global_load_dword v138, v[12:13], off offset:2048
	global_load_dword v139, v[10:11], off offset:512
	v_lshl_add_u64 v[10:11], s[2:3], 0, v[6:7]
	global_load_dword v140, v[14:15], off offset:2048
	global_load_dword v141, v[10:11], off offset:512
	v_mov_b32_e32 v11, v0
	v_or_b32_e32 v10, 0x300, v16
	v_lshl_add_u64 v[10:11], v[2:3], 0, v[10:11]
	v_lshlrev_b64 v[16:17], 2, v[10:11]
	v_lshl_add_u64 v[18:19], s[12:13], 0, v[16:17]
	global_load_dword v142, v[12:13], off offset:3072
	global_load_dword v143, v[18:19], off offset:512
	v_lshl_add_u64 v[12:13], s[2:3], 0, v[16:17]
	global_load_dword v144, v[14:15], off offset:3072
	global_load_dword v145, v[12:13], off offset:512
	v_add_u32_e32 v12, 0x1000, v34
	v_ashrrev_i32_e32 v13, 31, v12
	v_lshlrev_b64 v[12:13], 2, v[12:13]
	v_lshl_add_u64 v[14:15], s[12:13], 0, v[12:13]
	global_load_dword v146, v[14:15], off offset:512
	global_load_dword v147, v[14:15], off
	v_lshl_add_u64 v[14:15], s[2:3], 0, v[12:13]
	global_load_dword v148, v[14:15], off offset:512
	global_load_dword v149, v[14:15], off
	v_add_u32_e32 v14, 0x1100, v34
	v_ashrrev_i32_e32 v15, 31, v14
	v_lshlrev_b64 v[14:15], 2, v[14:15]
	v_lshl_add_u64 v[18:19], s[12:13], 0, v[14:15]
	v_lshl_add_u64 v[14:15], s[2:3], 0, v[14:15]
	global_load_dword v150, v[18:19], off offset:512
	global_load_dword v151, v[18:19], off
	global_load_dword v152, v[14:15], off offset:512
	global_load_dword v153, v[14:15], off
	v_add_u32_e32 v14, 0x1200, v34
	v_ashrrev_i32_e32 v15, 31, v14
	v_lshlrev_b64 v[14:15], 2, v[14:15]
	v_lshl_add_u64 v[18:19], s[12:13], 0, v[14:15]
	global_load_dword v160, v[18:19], off offset:512
	global_load_dword v161, v[18:19], off
	v_lshl_add_u64 v[18:19], s[2:3], 0, v[14:15]
	global_load_dword v162, v[18:19], off offset:512
	global_load_dword v163, v[18:19], off
	v_add_u32_e32 v18, 0x1300, v34
	v_ashrrev_i32_e32 v19, 31, v18
	v_lshlrev_b64 v[20:21], 2, v[18:19]
	v_lshl_add_u64 v[22:23], s[12:13], 0, v[20:21]
	v_lshl_add_u64 v[20:21], s[2:3], 0, v[20:21]
	global_load_dword v164, v[22:23], off offset:512
	global_load_dword v165, v[22:23], off
	global_load_dword v166, v[20:21], off offset:512
	global_load_dword v167, v[20:21], off
	v_add_u32_e32 v20, 0x2000, v34
	v_ashrrev_i32_e32 v21, 31, v20
	v_lshlrev_b64 v[20:21], 2, v[20:21]
	v_lshl_add_u64 v[22:23], s[12:13], 0, v[20:21]
	s_waitcnt vmcnt(0)
; #define LAS __attribute__((address_space(3)))
; __device__ __forceinline__ unsigned cvt_pk_bf16(float lo, float hi) { unsigned r; asm volatile("v_cvt_pk_bf16_f32 %0, %1, %2" : "=v"(r) : "v"(lo), "v"(hi)); return r; }
; __device__ __forceinline__ void lds_barrier() { asm volatile("s_waitcnt lgkmcnt(0)" ::: "memory"); __builtin_amdgcn_s_barrier(); asm volatile("" ::: "memory"); }
; __device__ __forceinline__ void lru_item(const Args& a, int l, int item, LAS unsigned char* lds) {
;     ...
;         const float* wa = a.in[15] + (pbase * 8 + hd) * 128 * 128; const float* wx = a.in[17] + (pbase * 8 + hd) * 128 * 128;
;         const int n = 16 * wave + fr;
; #pragma unroll
;         for (int ks = 0; ks < 4; ++ks) {
;             unsigned pa[4], px[4];
; #pragma unroll
;             for (int e = 0; e < 4; ++e) { const int k = 32 * ks + 8 * fq + 2 * e;
;                 pa[e] = cvt_pk_bf16(wa[k * 128 + n], wa[(k + 1) * 128 + n]); px[e] = cvt_pk_bf16(wx[k * 128 + n], wx[(k + 1) * 128 + n]); }
;             u32x4 ta = {pa[0], pa[1], pa[2], pa[3]}, tx = {px[0], px[1], px[2], px[3]};
;             wfa[ks] = __builtin_bit_cast(bf16x8, ta); wfx[ks] = __builtin_bit_cast(bf16x8, tx);
;         }
;     }
;     const int ecol = 16 * wave + fr;
;     const float e_ba = a.in[16][pbase * DLRU + hd * 128 + ecol], e_bx = a.in[18][pbase * DLRU + hd * 128 + ecol];
;     const float e_coef = -8.0f * log1pf(expf(-a.in[19][pbase * DLRU + hd * 128 + ecol]));
;     const int cg8 = (tid & 15) * 8, tg = (tid >> 4) & 15; const bool cvw = tid >= 256;
;     float cw[4][8], cb[8];
;     {
;         const float* cwp = a.in[13] + pbase * 4 * DLRU + hd * 128 + cg8; const float* cbp = a.in[14] + pbase * DLRU + hd * 128 + cg8;
; #pragma unroll
;         for (int k = 0; k < 4; ++k)
; #pragma unroll
;             for (int e = 0; e < 8; ++e) cw[k][e] = cwp[k * DLRU + e];
; #pragma unroll
;         for (int e = 0; e < 8; ++e) cb[e] = cbp[e];
;     }
;     const int xcol = 1536 + hd * 128;
;     float hstate = 0.f;
;     LAS unsigned char* At = lds + LRU_OFF_A; LAS unsigned char* HO = lds + LRU_OFF_HO;
;     LAS float* LA = (LAS float*)(lds + LRU_OFF_LA); LAS float* LB = (LAS float*)(lds + LRU_OFF_LB);
;     const int ntile = (L + 63) >> 6;
;     u32x4 raw[7];
;     lds_barrier();
;     if (cvw) { LRU_LOAD_RAW(0); LRU_CONV();
;     if (ntile > 1) LRU_LOAD_RAW(64); }
	v_cvt_pk_bf16_f32 v4, v131, v130
	v_cvt_pk_bf16_f32 v8, v133, v132
	v_cvt_pk_bf16_f32 v5, v134, v135
	v_cvt_pk_bf16_f32 v9, v136, v137
	v_cvt_pk_bf16_f32 v6, v138, v139
	v_cvt_pk_bf16_f32 v10, v140, v141
	v_cvt_pk_bf16_f32 v7, v142, v143
	v_cvt_pk_bf16_f32 v11, v144, v145
	v_cvt_pk_bf16_f32 v12, v147, v146
	v_cvt_pk_bf16_f32 v16, v149, v148
	v_cvt_pk_bf16_f32 v13, v151, v150
	v_cvt_pk_bf16_f32 v17, v153, v152
	v_cvt_pk_bf16_f32 v14, v161, v160
	v_cvt_pk_bf16_f32 v18, v163, v162
	v_cvt_pk_bf16_f32 v15, v165, v164
	v_cvt_pk_bf16_f32 v19, v167, v166
	global_load_dword v168, v[22:23], off offset:512
	global_load_dword v169, v[22:23], off
	v_lshl_add_u64 v[22:23], s[2:3], 0, v[20:21]
	global_load_dword v170, v[22:23], off offset:512
	global_load_dword v171, v[22:23], off
	v_add_u32_e32 v22, 0x2100, v34
	v_ashrrev_i32_e32 v23, 31, v22
	v_lshlrev_b64 v[22:23], 2, v[22:23]
	v_lshl_add_u64 v[26:27], s[12:13], 0, v[22:23]
	v_lshl_add_u64 v[22:23], s[2:3], 0, v[22:23]
	global_load_dword v172, v[26:27], off offset:512
	global_load_dword v173, v[26:27], off
	global_load_dword v174, v[22:23], off offset:512
	global_load_dword v175, v[22:23], off
	v_add_u32_e32 v22, 0x2200, v34
	v_ashrrev_i32_e32 v23, 31, v22
	v_lshlrev_b64 v[22:23], 2, v[22:23]
	v_lshl_add_u64 v[26:27], s[12:13], 0, v[22:23]
	global_load_dword v176, v[26:27], off offset:512
	global_load_dword v177, v[26:27], off
	v_lshl_add_u64 v[26:27], s[2:3], 0, v[22:23]
	global_load_dword v178, v[26:27], off offset:512
	global_load_dword v179, v[26:27], off
	v_add_u32_e32 v26, 0x2300, v34
	v_ashrrev_i32_e32 v27, 31, v26
	v_lshlrev_b64 v[28:29], 2, v[26:27]
	v_lshl_add_u64 v[30:31], s[12:13], 0, v[28:29]
	v_lshl_add_u64 v[28:29], s[2:3], 0, v[28:29]
	global_load_dword v180, v[30:31], off offset:512
	global_load_dword v181, v[30:31], off
	global_load_dword v182, v[28:29], off offset:512
	global_load_dword v183, v[28:29], off
	v_add_u32_e32 v28, 0x3000, v34
	v_ashrrev_i32_e32 v29, 31, v28
	v_lshlrev_b64 v[28:29], 2, v[28:29]
	v_lshl_add_u64 v[30:31], s[12:13], 0, v[28:29]
	global_load_dword v184, v[30:31], off offset:512
	global_load_dword v185, v[30:31], off
	v_lshl_add_u64 v[30:31], s[2:3], 0, v[28:29]
	global_load_dword v186, v[30:31], off offset:512
	global_load_dword v187, v[30:31], off
	v_add_u32_e32 v30, 0x3100, v34
	v_ashrrev_i32_e32 v31, 31, v30
	v_lshlrev_b64 v[30:31], 2, v[30:31]
	v_lshl_add_u64 v[36:37], s[12:13], 0, v[30:31]
	v_lshl_add_u64 v[30:31], s[2:3], 0, v[30:31]
	global_load_dword v188, v[36:37], off offset:512
	global_load_dword v189, v[36:37], off
	global_load_dword v190, v[30:31], off offset:512
	global_load_dword v191, v[30:31], off
	v_add_u32_e32 v30, 0x3200, v34
	v_ashrrev_i32_e32 v31, 31, v30
	v_lshlrev_b64 v[30:31], 2, v[30:31]
	v_lshl_add_u64 v[36:37], s[12:13], 0, v[30:31]
	v_add_u32_e32 v34, 0x3300, v34
	global_load_dword v192, v[36:37], off offset:512
	global_load_dword v193, v[36:37], off
	v_lshl_add_u64 v[36:37], s[2:3], 0, v[30:31]
	global_load_dword v194, v[36:37], off offset:512
	global_load_dword v195, v[36:37], off
	v_ashrrev_i32_e32 v35, 31, v34
	v_lshlrev_b64 v[36:37], 2, v[34:35]
	v_lshl_add_u64 v[38:39], s[12:13], 0, v[36:37]
	v_lshl_add_u64 v[36:37], s[2:3], 0, v[36:37]
	s_lshl_b64 s[2:3], s[0:1], 10
	s_or_b32 s2, s2, s6
	s_add_u32 s8, s62, s8
	s_addc_u32 s9, s63, s9
	s_lshl_b32 s7, s7, 9
	global_load_dword v196, v[38:39], off offset:512
	global_load_dword v197, v[38:39], off
	global_load_dword v210, v[36:37], off offset:512
	global_load_dword v211, v[36:37], off
	v_lshlrev_b32_e32 v36, 3, v1
	v_and_b32_e32 v60, 0x78, v36
	v_lshl_add_u64 v[36:37], s[2:3], 0, v[2:3]
	s_add_u32 s2, s8, s7
	v_lshlrev_b32_e32 v56, 2, v60
	s_addc_u32 s3, s9, 0
	v_lshl_add_u64 v[42:43], s[2:3], 0, v[56:57]
	s_mov_b64 s[8:9], 0x1000
	v_lshl_add_u64 v[48:49], v[42:43], 0, s[8:9]
	s_movk_i32 s8, 0x2000
	v_add_co_u32_e32 v44, vcc, s8, v42
	s_mov_b64 s[8:9], 0x2000
	s_lshl_b64 s[0:1], s[0:1], 12
	v_lshl_add_u64 v[50:51], v[42:43], 0, s[8:9]
	s_mov_b64 s[8:9], 0x3000
	s_add_u32 s0, s64, s0
	v_addc_co_u32_e32 v45, vcc, 0, v43, vcc
	v_lshl_add_u64 v[52:53], v[42:43], 0, s[8:9]
	s_movk_i32 s8, 0x3000
	v_lshlrev_b64 v[36:37], 2, v[36:37]
	s_addc_u32 s1, s65, s1
	v_add_co_u32_e32 v54, vcc, s8, v42
	v_lshl_add_u64 v[38:39], s[40:41], 0, v[36:37]
	v_lshl_add_u64 v[40:41], s[44:45], 0, v[36:37]
	v_lshl_add_u64 v[36:37], s[46:47], 0, v[36:37]
	v_addc_co_u32_e32 v55, vcc, 0, v43, vcc
	s_add_u32 s0, s0, s7
	s_addc_u32 s1, s1, 0
	s_waitcnt vmcnt(0)
	v_cvt_pk_bf16_f32 v20, v169, v168
	v_cvt_pk_bf16_f32 v24, v171, v170
	v_cvt_pk_bf16_f32 v21, v173, v172
	v_cvt_pk_bf16_f32 v25, v175, v174
	v_cvt_pk_bf16_f32 v22, v177, v176
	v_cvt_pk_bf16_f32 v26, v179, v178
	v_cvt_pk_bf16_f32 v23, v181, v180
	v_cvt_pk_bf16_f32 v27, v183, v182
	v_cvt_pk_bf16_f32 v28, v185, v184
	v_cvt_pk_bf16_f32 v32, v187, v186
	v_cvt_pk_bf16_f32 v29, v189, v188
	v_cvt_pk_bf16_f32 v33, v191, v190
	v_cvt_pk_bf16_f32 v30, v193, v192
	v_cvt_pk_bf16_f32 v34, v195, v194
	v_cvt_pk_bf16_f32 v31, v197, v196
	v_cvt_pk_bf16_f32 v35, v211, v210
	global_load_dword v122, v[38:39], off
	global_load_dword v123, v[40:41], off
	global_load_dword v125, v[36:37], off
	s_nop 0
	global_load_dwordx4 v[36:39], v56, s[2:3]
	global_load_dwordx4 v[40:43], v56, s[2:3] offset:16
	global_load_dwordx4 v[88:91], v[44:45], off offset:-4096
	s_nop 0
	global_load_dwordx4 v[44:47], v[44:45], off
	s_nop 0
	global_load_dwordx4 v[92:95], v[48:49], off offset:16
	s_nop 0
	global_load_dwordx4 v[48:51], v[50:51], off offset:16
	s_nop 0
	global_load_dwordx4 v[100:103], v[54:55], off
	global_load_dwordx4 v[96:99], v[52:53], off offset:16
	s_nop 0
	global_load_dwordx4 v[52:55], v56, s[0:1]
	s_nop 0
	global_load_dwordx4 v[56:59], v56, s[0:1] offset:16
	s_lshl_b32 s1, s4, 12
	s_lshl_b32 s0, s4, 11
	s_addk_i32 s1, 0x8000
	s_waitcnt lgkmcnt(0)
	s_barrier
	s_cmp_lt_i32 s4, 16
	s_cselect_b32 s12, 0x810, s36
	v_cmp_lt_i32_e32 vcc, s37, v1
	v_cmp_gt_i32_e64 s[40:41], s79, v1
	s_cselect_b32 s13, s0, s1
	v_lshlrev_b32_e32 v120, 1, v60
	v_mul_u32_u24_e32 v3, 0x440, v127
	s_and_saveexec_b64 s[0:1], s[40:41]
	s_xor_b64 s[0:1], exec, s[0:1]
	s_cbranch_execz .LBB0_197
	v_lshlrev_b32_e32 v128, 1, v60
	v_mul_u32_u24_e32 v3, 0x440, v127
	s_waitcnt vmcnt(4)
	v_mov_b32_e32 v118, v50
	s_waitcnt vmcnt(2)
	v_mov_b32_e32 v119, v98
	v_mov_b32_e32 v50, v99
	v_mov_b32_e32 v110, v42
	v_mov_b32_e32 v111, v94
	v_mov_b32_e32 v42, v95
	v_mov_b32_e32 v116, v48
	v_mov_b32_e32 v117, v96
	v_mov_b32_e32 v48, v97
	v_mov_b32_e32 v108, v40
	v_mov_b32_e32 v109, v92
	v_mov_b32_e32 v40, v93
	v_mov_b32_e32 v114, v46
	v_mov_b32_e32 v115, v102
	v_mov_b32_e32 v46, v103
	v_mov_b32_e32 v106, v38
	v_mov_b32_e32 v107, v90
	v_mov_b32_e32 v38, v91
	v_mov_b32_e32 v112, v44
	v_mov_b32_e32 v113, v100
	v_mov_b32_e32 v44, v101
	v_mov_b32_e32 v104, v36
	v_mov_b32_e32 v105, v88
	v_mov_b32_e32 v36, v89

; __device__ __forceinline__ unsigned cvt_pk_bf16(float lo, float hi) { unsigned r; asm volatile("v_cvt_pk_bf16_f32 %0, %1, %2" : "=v"(r) : "v"(lo), "v"(hi)); return r; }
; __device__ __forceinline__ int ltid() { int t = threadIdx.x; asm volatile("" : "+v"(t)); return t; }
; __device__ __forceinline__ void lru_item(const Args& a, int l, int item, LAS unsigned char* lds) {
;     const int tid = ltid(), lane = tid & 63, wave = __builtin_amdgcn_readfirstlane(tid >> 6), fr = lane & 15, fq = lane >> 4;
;     int s, rem;
;     if (item < 64) { s = 16 + (item >> 4); rem = item & 15; } else { s = (item - 64) >> 4; rem = (item - 64) & 15; }
;     const int hd = rem >> 1, dir = rem & 1, L = seq_len(s);
;     const bf16_t* proj = (const bf16_t*)(a.ws + WS_BIG);
;     bf16_t* hfb = (bf16_t*)(a.ws + WS_BIG + BIG_HFB);
;     const size_t pbase = (size_t)(l * 2 + dir);
;     bf16x8 wfa[4], wfx[4];
;     {
;         const float* wa = a.in[15] + (pbase * 8 + hd) * 128 * 128; const float* wx = a.in[17] + (pbase * 8 + hd) * 128 * 128;
;         const int n = 16 * wave + fr;
; #pragma unroll
;         for (int ks = 0; ks < 4; ++ks) {
;             unsigned pa[4], px[4];
; #pragma unroll
;             for (int e = 0; e < 4; ++e) { const int k = 32 * ks + 8 * fq + 2 * e;
;                 pa[e] = cvt_pk_bf16(wa[k * 128 + n], wa[(k + 1) * 128 + n]); px[e] = cvt_pk_bf16(wx[k * 128 + n], wx[(k + 1) * 128 + n]); }
.LBB0_240:
	s_and_b64 vcc, exec, s[0:1]
	s_cbranch_vccz .LBB0_325
	s_ashr_i32 s0, s30, 4
	s_sub_i32 s1, s30, 64
	s_add_i32 s0, s0, 16
	s_lshr_b32 s1, s1, 4
	s_cmp_lt_i32 s30, 64
	s_cselect_b32 s4, s0, s1
	s_and_b32 s5, s30, 1
	s_or_b32 s0, s5, s31
	v_writelane_b32 v251, s94, 20
	s_bfe_u32 s7, s30, 0x30001
	s_ashr_i32 s1, s0, 31
	v_writelane_b32 v251, s95, 21
	s_lshl_b64 s[2:3], s[0:1], 19
	s_lshl_b32 s8, s7, 16
	v_readlane_b32 s80, v254, 23
	s_or_b32 s2, s2, s8
	v_readlane_b32 s94, v254, 37
	v_readlane_b32 s95, v254, 38
	s_add_u32 s20, s94, s2
	v_mov_b32_e32 v1, v155
	s_addc_u32 s21, s95, s3
	s_add_u32 s2, s54, s2
	v_readfirstlane_b32 s6, v1
	v_bfe_u32 v124, v1, 4, 2
	s_addc_u32 s3, s55, s3
	s_ashr_i32 s6, s6, 2
	v_bfi_b32 v2, -16, s6, v1
	v_lshlrev_b32_e32 v16, 10, v124
	v_add_u32_e32 v34, v2, v16
	v_ashrrev_i32_e32 v35, 31, v34
	v_lshlrev_b64 v[4:5], 2, v[34:35]
	v_lshl_add_u64 v[12:13], s[20:21], 0, v[4:5]
	global_load_dword v130, v[12:13], off offset:512
	global_load_dword v131, v[12:13], off
	v_lshl_add_u64 v[14:15], s[2:3], 0, v[4:5]
	v_mov_b32_e32 v7, v0
	s_lshl_b64 s[10:11], s[0:1], 10
	s_lshl_b32 s6, s7, 7
	v_readlane_b32 s90, v254, 33
	s_lshl_b64 s[8:9], s[0:1], 14
	s_or_b32 s10, s10, s6
	v_readlane_b32 s91, v254, 34
	s_add_u32 s8, s90, s8
	s_addc_u32 s9, s91, s9
	s_lshl_b32 s7, s7, 9
	v_readlane_b32 s81, v254, 24
	s_add_u32 s80, s8, s7
	v_mov_b32_e32 v57, v0
	s_addc_u32 s81, s9, 0
	s_mov_b64 s[8:9], 0x1000
	v_readlane_b32 s92, v254, 35
	s_lshl_b64 s[0:1], s[0:1], 12
	s_mov_b32 s16, s50
	v_readlane_b32 s93, v254, 36
	s_mov_b64 s[40:41], s[52:53]
	v_writelane_b32 v251, s10, 22
	s_add_u32 s0, s92, s0
	s_mov_b64 s[44:45], s[56:57]
	s_mov_b64 s[46:47], s[58:59]
	s_mov_b64 s[48:49], s[60:61]
	s_addc_u32 s1, s93, s1
	s_add_u32 s48, s0, s7
	s_addc_u32 s49, s1, 0
	s_lshl_b32 s1, s4, 12
	s_lshl_b32 s0, s4, 11
	s_addk_i32 s1, 0x8000
	s_cmp_lt_i32 s4, 16
	v_bfe_u32 v127, v1, 4, 4
	s_mov_b32 s18, s71
	s_mov_b32 s17, s68
	s_cselect_b32 s36, 0x810, s36
	v_readlane_b32 s82, v254, 25
	v_readlane_b32 s83, v254, 26
	v_readlane_b32 s84, v254, 27
	v_readlane_b32 s85, v254, 28
	v_readlane_b32 s86, v254, 29
	v_readlane_b32 s87, v254, 30
	v_readlane_b32 s88, v254, 31
	v_readlane_b32 s89, v254, 32
	s_mov_b64 s[42:43], s[54:55]
	s_mov_b64 s[50:51], s[62:63]
	s_mov_b64 s[52:53], s[64:65]
	s_mov_b64 s[54:55], s[66:67]
	v_writelane_b32 v251, s11, 23
	global_load_dword v132, v[14:15], off offset:512
	global_load_dword v133, v[14:15], off
	v_or_b32_e32 v6, 0x100, v16
	v_ashrrev_i32_e32 v3, 31, v2
	v_lshl_add_u64 v[6:7], v[2:3], 0, v[6:7]
	v_lshlrev_b64 v[6:7], 2, v[6:7]
	v_lshl_add_u64 v[10:11], s[20:21], 0, v[6:7]
	v_lshl_add_u64 v[6:7], s[2:3], 0, v[6:7]
	global_load_dword v134, v[12:13], off offset:1024
	global_load_dword v135, v[10:11], off offset:512
	global_load_dword v136, v[14:15], off offset:1024
	global_load_dword v137, v[6:7], off offset:512
	v_mov_b32_e32 v7, v0
	v_or_b32_e32 v6, 0x200, v16
	v_lshl_add_u64 v[6:7], v[2:3], 0, v[6:7]
	v_lshlrev_b64 v[6:7], 2, v[6:7]
	v_lshl_add_u64 v[10:11], s[20:21], 0, v[6:7]
	global_load_dword v138, v[12:13], off offset:2048
	global_load_dword v139, v[10:11], off offset:512
	v_lshl_add_u64 v[10:11], s[2:3], 0, v[6:7]
	global_load_dword v140, v[14:15], off offset:2048
	global_load_dword v141, v[10:11], off offset:512
	v_mov_b32_e32 v11, v0
	v_or_b32_e32 v10, 0x300, v16
	v_lshl_add_u64 v[10:11], v[2:3], 0, v[10:11]
	v_lshlrev_b64 v[16:17], 2, v[10:11]
	v_lshl_add_u64 v[18:19], s[20:21], 0, v[16:17]
	global_load_dword v142, v[12:13], off offset:3072
	global_load_dword v143, v[18:19], off offset:512
	v_lshl_add_u64 v[12:13], s[2:3], 0, v[16:17]
	global_load_dword v144, v[14:15], off offset:3072
	global_load_dword v145, v[12:13], off offset:512
	v_add_u32_e32 v12, 0x1000, v34
	v_ashrrev_i32_e32 v13, 31, v12
	v_lshlrev_b64 v[12:13], 2, v[12:13]
	v_lshl_add_u64 v[14:15], s[20:21], 0, v[12:13]
	global_load_dword v146, v[14:15], off offset:512
	global_load_dword v147, v[14:15], off
	v_lshl_add_u64 v[14:15], s[2:3], 0, v[12:13]
	global_load_dword v148, v[14:15], off offset:512
	global_load_dword v149, v[14:15], off
	v_add_u32_e32 v14, 0x1100, v34
	v_ashrrev_i32_e32 v15, 31, v14
	v_lshlrev_b64 v[14:15], 2, v[14:15]
	v_lshl_add_u64 v[18:19], s[20:21], 0, v[14:15]
	v_lshl_add_u64 v[14:15], s[2:3], 0, v[14:15]
	global_load_dword v150, v[18:19], off offset:512
	global_load_dword v151, v[18:19], off
	global_load_dword v152, v[14:15], off offset:512
	global_load_dword v153, v[14:15], off
	v_add_u32_e32 v14, 0x1200, v34
	v_ashrrev_i32_e32 v15, 31, v14
	v_lshlrev_b64 v[14:15], 2, v[14:15]
	v_lshl_add_u64 v[18:19], s[20:21], 0, v[14:15]
	global_load_dword v160, v[18:19], off offset:512
	global_load_dword v161, v[18:19], off
	v_lshl_add_u64 v[18:19], s[2:3], 0, v[14:15]
	global_load_dword v162, v[18:19], off offset:512
	global_load_dword v163, v[18:19], off
	v_add_u32_e32 v18, 0x1300, v34
	v_ashrrev_i32_e32 v19, 31, v18
	v_lshlrev_b64 v[20:21], 2, v[18:19]
	v_lshl_add_u64 v[22:23], s[20:21], 0, v[20:21]
	v_lshl_add_u64 v[20:21], s[2:3], 0, v[20:21]
	global_load_dword v164, v[22:23], off offset:512
	global_load_dword v165, v[22:23], off
	global_load_dword v166, v[20:21], off offset:512
	global_load_dword v167, v[20:21], off
	v_add_u32_e32 v20, 0x2000, v34
	v_ashrrev_i32_e32 v21, 31, v20
	v_lshlrev_b64 v[20:21], 2, v[20:21]
	v_lshl_add_u64 v[22:23], s[20:21], 0, v[20:21]
	s_waitcnt vmcnt(0)
; #define LAS __attribute__((address_space(3)))
; __device__ __forceinline__ unsigned cvt_pk_bf16(float lo, float hi) { unsigned r; asm volatile("v_cvt_pk_bf16_f32 %0, %1, %2" : "=v"(r) : "v"(lo), "v"(hi)); return r; }
; __device__ __forceinline__ void lds_barrier() { asm volatile("s_waitcnt lgkmcnt(0)" ::: "memory"); __builtin_amdgcn_s_barrier(); asm volatile("" ::: "memory"); }
; __device__ __forceinline__ void lru_item(const Args& a, int l, int item, LAS unsigned char* lds) {
;     ...
;         const float* wa = a.in[15] + (pbase * 8 + hd) * 128 * 128; const float* wx = a.in[17] + (pbase * 8 + hd) * 128 * 128;
;         const int n = 16 * wave + fr;
; #pragma unroll
;         for (int ks = 0; ks < 4; ++ks) {
;             unsigned pa[4], px[4];
; #pragma unroll
;             for (int e = 0; e < 4; ++e) { const int k = 32 * ks + 8 * fq + 2 * e;
;                 pa[e] = cvt_pk_bf16(wa[k * 128 + n], wa[(k + 1) * 128 + n]); px[e] = cvt_pk_bf16(wx[k * 128 + n], wx[(k + 1) * 128 + n]); }
;             u32x4 ta = {pa[0], pa[1], pa[2], pa[3]}, tx = {px[0], px[1], px[2], px[3]};
;             wfa[ks] = __builtin_bit_cast(bf16x8, ta); wfx[ks] = __builtin_bit_cast(bf16x8, tx);
;         }
;     }
;     const int ecol = 16 * wave + fr;
;     const float e_ba = a.in[16][pbase * DLRU + hd * 128 + ecol], e_bx = a.in[18][pbase * DLRU + hd * 128 + ecol];
;     const float e_coef = -8.0f * log1pf(expf(-a.in[19][pbase * DLRU + hd * 128 + ecol]));
;     const int cg8 = (tid & 15) * 8, tg = (tid >> 4) & 15; const bool cvw = tid >= 256;
;     float cw[4][8], cb[8];
;     {
;         const float* cwp = a.in[13] + pbase * 4 * DLRU + hd * 128 + cg8; const float* cbp = a.in[14] + pbase * DLRU + hd * 128 + cg8;
; #pragma unroll
;         for (int k = 0; k < 4; ++k)
; #pragma unroll
;             for (int e = 0; e < 8; ++e) cw[k][e] = cwp[k * DLRU + e];
; #pragma unroll
;         for (int e = 0; e < 8; ++e) cb[e] = cbp[e];
;     }
;     const int xcol = 1536 + hd * 128;
;     float hstate = 0.f;
;     LAS unsigned char* At = lds + LRU_OFF_A; LAS unsigned char* HO = lds + LRU_OFF_HO;
;     LAS float* LA = (LAS float*)(lds + LRU_OFF_LA); LAS float* LB = (LAS float*)(lds + LRU_OFF_LB);
;     const int ntile = (L + 63) >> 6;
;     u32x4 raw[7];
;     lds_barrier();
;     if (cvw) { LRU_LOAD_RAW(0); LRU_CONV();
;     if (ntile > 1) LRU_LOAD_RAW(64); }
	v_cvt_pk_bf16_f32 v4, v131, v130
	v_cvt_pk_bf16_f32 v8, v133, v132
	v_cvt_pk_bf16_f32 v5, v134, v135
	v_cvt_pk_bf16_f32 v9, v136, v137
	v_cvt_pk_bf16_f32 v6, v138, v139
	v_cvt_pk_bf16_f32 v10, v140, v141
	v_cvt_pk_bf16_f32 v7, v142, v143
	v_cvt_pk_bf16_f32 v11, v144, v145
	v_cvt_pk_bf16_f32 v12, v147, v146
	v_cvt_pk_bf16_f32 v16, v149, v148
	v_cvt_pk_bf16_f32 v13, v151, v150
	v_cvt_pk_bf16_f32 v17, v153, v152
	v_cvt_pk_bf16_f32 v14, v161, v160
	v_cvt_pk_bf16_f32 v18, v163, v162
	v_cvt_pk_bf16_f32 v15, v165, v164
	v_cvt_pk_bf16_f32 v19, v167, v166
	global_load_dword v168, v[22:23], off offset:512
	global_load_dword v169, v[22:23], off
	v_lshl_add_u64 v[22:23], s[2:3], 0, v[20:21]
	global_load_dword v170, v[22:23], off offset:512
	global_load_dword v171, v[22:23], off
	v_add_u32_e32 v22, 0x2100, v34
	v_ashrrev_i32_e32 v23, 31, v22
	v_lshlrev_b64 v[22:23], 2, v[22:23]
	v_lshl_add_u64 v[26:27], s[20:21], 0, v[22:23]
	v_lshl_add_u64 v[22:23], s[2:3], 0, v[22:23]
	global_load_dword v172, v[26:27], off offset:512
	global_load_dword v173, v[26:27], off
	global_load_dword v174, v[22:23], off offset:512
	global_load_dword v175, v[22:23], off
	v_add_u32_e32 v22, 0x2200, v34
	v_ashrrev_i32_e32 v23, 31, v22
	v_lshlrev_b64 v[22:23], 2, v[22:23]
	v_lshl_add_u64 v[26:27], s[20:21], 0, v[22:23]
	global_load_dword v176, v[26:27], off offset:512
	global_load_dword v177, v[26:27], off
	v_lshl_add_u64 v[26:27], s[2:3], 0, v[22:23]
	global_load_dword v178, v[26:27], off offset:512
	global_load_dword v179, v[26:27], off
	v_add_u32_e32 v26, 0x2300, v34
	v_ashrrev_i32_e32 v27, 31, v26
	v_lshlrev_b64 v[28:29], 2, v[26:27]
	v_lshl_add_u64 v[30:31], s[20:21], 0, v[28:29]
	v_lshl_add_u64 v[28:29], s[2:3], 0, v[28:29]
	global_load_dword v180, v[30:31], off offset:512
	global_load_dword v181, v[30:31], off
	global_load_dword v182, v[28:29], off offset:512
	global_load_dword v183, v[28:29], off
	v_add_u32_e32 v28, 0x3000, v34
	v_ashrrev_i32_e32 v29, 31, v28
	v_lshlrev_b64 v[28:29], 2, v[28:29]
	v_lshl_add_u64 v[30:31], s[20:21], 0, v[28:29]
	global_load_dword v184, v[30:31], off offset:512
	global_load_dword v185, v[30:31], off
	v_lshl_add_u64 v[30:31], s[2:3], 0, v[28:29]
	global_load_dword v186, v[30:31], off offset:512
	global_load_dword v187, v[30:31], off
	v_add_u32_e32 v30, 0x3100, v34
	v_ashrrev_i32_e32 v31, 31, v30
	v_lshlrev_b64 v[30:31], 2, v[30:31]
	v_lshl_add_u64 v[36:37], s[20:21], 0, v[30:31]
	v_lshl_add_u64 v[30:31], s[2:3], 0, v[30:31]
	global_load_dword v188, v[36:37], off offset:512
	global_load_dword v189, v[36:37], off
	global_load_dword v190, v[30:31], off offset:512
	global_load_dword v191, v[30:31], off
	v_add_u32_e32 v30, 0x3200, v34
	v_ashrrev_i32_e32 v31, 31, v30
	v_lshlrev_b64 v[30:31], 2, v[30:31]
	v_lshl_add_u64 v[36:37], s[20:21], 0, v[30:31]
	v_add_u32_e32 v34, 0x3300, v34
	global_load_dword v192, v[36:37], off offset:512
	global_load_dword v193, v[36:37], off
	v_lshl_add_u64 v[36:37], s[2:3], 0, v[30:31]
	global_load_dword v194, v[36:37], off offset:512
	global_load_dword v195, v[36:37], off
	v_ashrrev_i32_e32 v35, 31, v34
	v_lshlrev_b64 v[36:37], 2, v[34:35]
	v_lshl_add_u64 v[38:39], s[20:21], 0, v[36:37]
	v_lshl_add_u64 v[36:37], s[2:3], 0, v[36:37]
	global_load_dword v196, v[38:39], off offset:512
	global_load_dword v197, v[38:39], off
	global_load_dword v210, v[36:37], off offset:512
	global_load_dword v211, v[36:37], off
	v_lshlrev_b32_e32 v36, 3, v1
	v_and_b32_e32 v60, 0x78, v36
	v_lshlrev_b32_e32 v56, 2, v60
	v_lshl_add_u64 v[42:43], s[80:81], 0, v[56:57]
	v_lshl_add_u64 v[48:49], v[42:43], 0, s[8:9]
	s_movk_i32 s8, 0x2000
	v_add_co_u32_e32 v44, vcc, s8, v42
	s_mov_b64 s[8:9], 0x2000
	v_lshl_add_u64 v[50:51], v[42:43], 0, s[8:9]
	s_mov_b64 s[8:9], 0x3000
	v_lshl_add_u64 v[36:37], s[10:11], 0, v[2:3]
	v_addc_co_u32_e32 v45, vcc, 0, v43, vcc
	v_lshl_add_u64 v[52:53], v[42:43], 0, s[8:9]
	s_movk_i32 s8, 0x3000
	v_lshlrev_b64 v[36:37], 2, v[36:37]
	v_add_co_u32_e32 v54, vcc, s8, v42
	v_lshl_add_u64 v[38:39], s[40:41], 0, v[36:37]
	v_lshl_add_u64 v[40:41], s[44:45], 0, v[36:37]
	v_lshl_add_u64 v[36:37], s[46:47], 0, v[36:37]
	v_addc_co_u32_e32 v55, vcc, 0, v43, vcc
	v_cmp_lt_i32_e64 s[40:41], s37, v1
	v_cmp_gt_i32_e32 vcc, s79, v1
	s_cselect_b32 s37, s0, s1
	v_lshlrev_b32_e32 v120, 1, v60
	v_mul_u32_u24_e32 v3, 0x440, v127
	s_waitcnt vmcnt(0)
	v_cvt_pk_bf16_f32 v20, v169, v168
	v_cvt_pk_bf16_f32 v24, v171, v170
	v_cvt_pk_bf16_f32 v21, v173, v172
	v_cvt_pk_bf16_f32 v25, v175, v174
	v_cvt_pk_bf16_f32 v22, v177, v176
	v_cvt_pk_bf16_f32 v26, v179, v178
	v_cvt_pk_bf16_f32 v23, v181, v180
	v_cvt_pk_bf16_f32 v27, v183, v182
	v_cvt_pk_bf16_f32 v28, v185, v184
	v_cvt_pk_bf16_f32 v32, v187, v186
	v_cvt_pk_bf16_f32 v29, v189, v188
	v_cvt_pk_bf16_f32 v33, v191, v190
	v_cvt_pk_bf16_f32 v30, v193, v192
	v_cvt_pk_bf16_f32 v34, v195, v194
	v_cvt_pk_bf16_f32 v31, v197, v196
	v_cvt_pk_bf16_f32 v35, v211, v210
	global_load_dword v122, v[38:39], off
	global_load_dword v123, v[40:41], off
	global_load_dword v125, v[36:37], off
	s_nop 0
	global_load_dwordx4 v[36:39], v56, s[80:81]
	global_load_dwordx4 v[40:43], v56, s[80:81] offset:16
	global_load_dwordx4 v[88:91], v[44:45], off offset:-4096
	s_nop 0
	global_load_dwordx4 v[44:47], v[44:45], off
	s_nop 0
	global_load_dwordx4 v[92:95], v[48:49], off offset:16
	s_nop 0
	global_load_dwordx4 v[48:51], v[50:51], off offset:16
	s_nop 0
	global_load_dwordx4 v[100:103], v[54:55], off
	global_load_dwordx4 v[96:99], v[52:53], off offset:16
	s_nop 0
	global_load_dwordx4 v[52:55], v56, s[48:49]
	s_nop 0
	global_load_dwordx4 v[56:59], v56, s[48:49] offset:16
	s_waitcnt lgkmcnt(0)
	s_barrier
	s_and_saveexec_b64 s[0:1], vcc
	s_xor_b64 s[0:1], exec, s[0:1]
	s_cbranch_execz .LBB0_243
	v_lshlrev_b32_e32 v128, 1, v60
	v_mul_u32_u24_e32 v3, 0x440, v127
	s_waitcnt vmcnt(4)
	v_mov_b32_e32 v118, v50
	s_waitcnt vmcnt(2)
	v_mov_b32_e32 v119, v98
	v_mov_b32_e32 v50, v99
	v_mov_b32_e32 v110, v42
	v_mov_b32_e32 v111, v94
	v_mov_b32_e32 v42, v95
	v_mov_b32_e32 v116, v48
	v_mov_b32_e32 v117, v96
	v_mov_b32_e32 v48, v97
	v_mov_b32_e32 v108, v40
	v_mov_b32_e32 v109, v92
	v_mov_b32_e32 v40, v93
	v_mov_b32_e32 v114, v46
	v_mov_b32_e32 v115, v102
	v_mov_b32_e32 v46, v103
	v_mov_b32_e32 v106, v38
	v_mov_b32_e32 v107, v90
	v_mov_b32_e32 v38, v91
	v_mov_b32_e32 v112, v44
	v_mov_b32_e32 v113, v100
	v_mov_b32_e32 v44, v101
	v_mov_b32_e32 v104, v36
	v_mov_b32_e32 v105, v88
	v_mov_b32_e32 v36, v89

; __device__ __forceinline__ unsigned cvt_pk_bf16(float lo, float hi) { unsigned r; asm volatile("v_cvt_pk_bf16_f32 %0, %1, %2" : "=v"(r) : "v"(lo), "v"(hi)); return r; }
; __device__ __forceinline__ int ltid() { int t = threadIdx.x; asm volatile("" : "+v"(t)); return t; }
; __device__ __forceinline__ void lru_item(const Args& a, int l, int item, LAS unsigned char* lds) {
;     const int tid = ltid(), lane = tid & 63, wave = __builtin_amdgcn_readfirstlane(tid >> 6), fr = lane & 15, fq = lane >> 4;
;     int s, rem;
;     if (item < 64) { s = 16 + (item >> 4); rem = item & 15; } else { s = (item - 64) >> 4; rem = (item - 64) & 15; }
;     const int hd = rem >> 1, dir = rem & 1, L = seq_len(s);
;     const bf16_t* proj = (const bf16_t*)(a.ws + WS_BIG);
;     bf16_t* hfb = (bf16_t*)(a.ws + WS_BIG + BIG_HFB);
;     const size_t pbase = (size_t)(l * 2 + dir);
;     bf16x8 wfa[4], wfx[4];
;     {
;         const float* wa = a.in[15] + (pbase * 8 + hd) * 128 * 128; const float* wx = a.in[17] + (pbase * 8 + hd) * 128 * 128;
;         const int n = 16 * wave + fr;
; #pragma unroll
;         for (int ks = 0; ks < 4; ++ks) {
;             unsigned pa[4], px[4];
; #pragma unroll
;             for (int e = 0; e < 4; ++e) { const int k = 32 * ks + 8 * fq + 2 * e;
;                 pa[e] = cvt_pk_bf16(wa[k * 128 + n], wa[(k + 1) * 128 + n]); px[e] = cvt_pk_bf16(wx[k * 128 + n], wx[(k + 1) * 128 + n]); }
; __device__ __forceinline__ void lru_phase(const Args& a, int l, LAS unsigned char* lds) {
;     ...
;     if (G == 256) { lru_item(a, l, b, lds); if (b >= 64 && b < 128) lru_item(a, l, b + 192, lds);
.LBB0_278:
	s_and_b32 s0, s30, 0xffffffc0
	v_readlane_b32 s16, v254, 43
	s_cmp_lg_u32 s0, 64
	v_readlane_b32 s17, v254, 44
	s_cbranch_scc1 .LBB0_314
	v_mov_b32_e32 v1, v155
	v_mov_b32_e32 v7, v0
	v_readfirstlane_b32 s0, v1
	v_bfe_u32 v124, v1, 4, 2
	s_ashr_i32 s0, s0, 2
	v_bfi_b32 v2, -16, s0, v1
	v_lshlrev_b32_e32 v16, 10, v124
	v_add_u32_e32 v34, v2, v16
	v_ashrrev_i32_e32 v35, 31, v34
	v_lshlrev_b64 v[4:5], 2, v[34:35]
	v_lshl_add_u64 v[12:13], s[20:21], 0, v[4:5]
	global_load_dword v130, v[12:13], off offset:512
	global_load_dword v131, v[12:13], off
	v_lshl_add_u64 v[14:15], s[2:3], 0, v[4:5]
	v_readlane_b32 s0, v251, 22
	s_waitcnt vmcnt(2)
	v_mov_b32_e32 v57, v0
	v_readlane_b32 s1, v251, 23
	v_bfe_u32 v86, v1, 4, 4
	global_load_dword v132, v[14:15], off offset:512
	global_load_dword v133, v[14:15], off
	v_or_b32_e32 v6, 0x100, v16
	v_ashrrev_i32_e32 v3, 31, v2
	v_lshl_add_u64 v[6:7], v[2:3], 0, v[6:7]
	v_lshlrev_b64 v[6:7], 2, v[6:7]
	v_lshl_add_u64 v[10:11], s[20:21], 0, v[6:7]
	v_lshl_add_u64 v[6:7], s[2:3], 0, v[6:7]
	global_load_dword v134, v[12:13], off offset:1024
	global_load_dword v135, v[10:11], off offset:512
	global_load_dword v136, v[14:15], off offset:1024
	global_load_dword v137, v[6:7], off offset:512
	v_mov_b32_e32 v7, v0
	v_or_b32_e32 v6, 0x200, v16
	v_lshl_add_u64 v[6:7], v[2:3], 0, v[6:7]
	v_lshlrev_b64 v[6:7], 2, v[6:7]
	v_lshl_add_u64 v[10:11], s[20:21], 0, v[6:7]
	global_load_dword v138, v[12:13], off offset:2048
	global_load_dword v139, v[10:11], off offset:512
	v_lshl_add_u64 v[10:11], s[2:3], 0, v[6:7]
	global_load_dword v140, v[14:15], off offset:2048
	global_load_dword v141, v[10:11], off offset:512
	v_mov_b32_e32 v11, v0
	v_or_b32_e32 v10, 0x300, v16
	v_lshl_add_u64 v[10:11], v[2:3], 0, v[10:11]
	v_lshlrev_b64 v[16:17], 2, v[10:11]
	v_lshl_add_u64 v[18:19], s[20:21], 0, v[16:17]
	global_load_dword v142, v[12:13], off offset:3072
	global_load_dword v143, v[18:19], off offset:512
	v_lshl_add_u64 v[12:13], s[2:3], 0, v[16:17]
	global_load_dword v144, v[14:15], off offset:3072
	global_load_dword v145, v[12:13], off offset:512
	v_add_u32_e32 v12, 0x1000, v34
	v_ashrrev_i32_e32 v13, 31, v12
	v_lshlrev_b64 v[12:13], 2, v[12:13]
	v_lshl_add_u64 v[14:15], s[20:21], 0, v[12:13]
	global_load_dword v146, v[14:15], off offset:512
	global_load_dword v147, v[14:15], off
	v_lshl_add_u64 v[14:15], s[2:3], 0, v[12:13]
	global_load_dword v148, v[14:15], off offset:512
	global_load_dword v149, v[14:15], off
	v_add_u32_e32 v14, 0x1100, v34
	v_ashrrev_i32_e32 v15, 31, v14
	v_lshlrev_b64 v[14:15], 2, v[14:15]
	v_lshl_add_u64 v[18:19], s[20:21], 0, v[14:15]
	v_lshl_add_u64 v[14:15], s[2:3], 0, v[14:15]
	global_load_dword v150, v[18:19], off offset:512
	global_load_dword v151, v[18:19], off
	global_load_dword v152, v[14:15], off offset:512
	global_load_dword v153, v[14:15], off
	v_add_u32_e32 v14, 0x1200, v34
	v_ashrrev_i32_e32 v15, 31, v14
	v_lshlrev_b64 v[14:15], 2, v[14:15]
	v_lshl_add_u64 v[18:19], s[20:21], 0, v[14:15]
	global_load_dword v160, v[18:19], off offset:512
	global_load_dword v161, v[18:19], off
	v_lshl_add_u64 v[18:19], s[2:3], 0, v[14:15]
	global_load_dword v162, v[18:19], off offset:512
	global_load_dword v163, v[18:19], off
	v_add_u32_e32 v18, 0x1300, v34
	v_ashrrev_i32_e32 v19, 31, v18
	v_lshlrev_b64 v[20:21], 2, v[18:19]
	v_lshl_add_u64 v[22:23], s[20:21], 0, v[20:21]
	v_lshl_add_u64 v[20:21], s[2:3], 0, v[20:21]
	global_load_dword v164, v[22:23], off offset:512
	global_load_dword v165, v[22:23], off
	global_load_dword v166, v[20:21], off offset:512
	global_load_dword v167, v[20:21], off
	v_add_u32_e32 v20, 0x2000, v34
	v_ashrrev_i32_e32 v21, 31, v20
	v_lshlrev_b64 v[20:21], 2, v[20:21]
	v_lshl_add_u64 v[22:23], s[20:21], 0, v[20:21]
	s_waitcnt vmcnt(0)
; #define LAS __attribute__((address_space(3)))
; __device__ __forceinline__ unsigned cvt_pk_bf16(float lo, float hi) { unsigned r; asm volatile("v_cvt_pk_bf16_f32 %0, %1, %2" : "=v"(r) : "v"(lo), "v"(hi)); return r; }
; __device__ __forceinline__ void lds_barrier() { asm volatile("s_waitcnt lgkmcnt(0)" ::: "memory"); __builtin_amdgcn_s_barrier(); asm volatile("" ::: "memory"); }
; __device__ __forceinline__ void lru_item(const Args& a, int l, int item, LAS unsigned char* lds) {
;     ...
;         const float* wa = a.in[15] + (pbase * 8 + hd) * 128 * 128; const float* wx = a.in[17] + (pbase * 8 + hd) * 128 * 128;
;         const int n = 16 * wave + fr;
; #pragma unroll
;         for (int ks = 0; ks < 4; ++ks) {
;             unsigned pa[4], px[4];
; #pragma unroll
;             for (int e = 0; e < 4; ++e) { const int k = 32 * ks + 8 * fq + 2 * e;
;                 pa[e] = cvt_pk_bf16(wa[k * 128 + n], wa[(k + 1) * 128 + n]); px[e] = cvt_pk_bf16(wx[k * 128 + n], wx[(k + 1) * 128 + n]); }
;             u32x4 ta = {pa[0], pa[1], pa[2], pa[3]}, tx = {px[0], px[1], px[2], px[3]};
;             wfa[ks] = __builtin_bit_cast(bf16x8, ta); wfx[ks] = __builtin_bit_cast(bf16x8, tx);
;         }
;     }
;     const int ecol = 16 * wave + fr;
;     const float e_ba = a.in[16][pbase * DLRU + hd * 128 + ecol], e_bx = a.in[18][pbase * DLRU + hd * 128 + ecol];
;     const float e_coef = -8.0f * log1pf(expf(-a.in[19][pbase * DLRU + hd * 128 + ecol]));
;     const int cg8 = (tid & 15) * 8, tg = (tid >> 4) & 15; const bool cvw = tid >= 256;
;     float cw[4][8], cb[8];
;     {
;         const float* cwp = a.in[13] + pbase * 4 * DLRU + hd * 128 + cg8; const float* cbp = a.in[14] + pbase * DLRU + hd * 128 + cg8;
; #pragma unroll
;         for (int k = 0; k < 4; ++k)
; #pragma unroll
;             for (int e = 0; e < 8; ++e) cw[k][e] = cwp[k * DLRU + e];
; #pragma unroll
;         for (int e = 0; e < 8; ++e) cb[e] = cbp[e];
;     }
;     const int xcol = 1536 + hd * 128;
;     float hstate = 0.f;
;     LAS unsigned char* At = lds + LRU_OFF_A; LAS unsigned char* HO = lds + LRU_OFF_HO;
;     LAS float* LA = (LAS float*)(lds + LRU_OFF_LA); LAS float* LB = (LAS float*)(lds + LRU_OFF_LB);
;     const int ntile = (L + 63) >> 6;
;     u32x4 raw[7];
;     lds_barrier();
;     if (cvw) { LRU_LOAD_RAW(0); LRU_CONV();
;     if (ntile > 1) LRU_LOAD_RAW(64); }
	v_cvt_pk_bf16_f32 v4, v131, v130
	v_cvt_pk_bf16_f32 v8, v133, v132
	v_cvt_pk_bf16_f32 v5, v134, v135
	v_cvt_pk_bf16_f32 v9, v136, v137
	v_cvt_pk_bf16_f32 v6, v138, v139
	v_cvt_pk_bf16_f32 v10, v140, v141
	v_cvt_pk_bf16_f32 v7, v142, v143
	v_cvt_pk_bf16_f32 v11, v144, v145
	v_cvt_pk_bf16_f32 v12, v147, v146
	v_cvt_pk_bf16_f32 v16, v149, v148
	v_cvt_pk_bf16_f32 v13, v151, v150
	v_cvt_pk_bf16_f32 v17, v153, v152
	v_cvt_pk_bf16_f32 v14, v161, v160
	v_cvt_pk_bf16_f32 v18, v163, v162
	v_cvt_pk_bf16_f32 v15, v165, v164
	v_cvt_pk_bf16_f32 v19, v167, v166
	global_load_dword v168, v[22:23], off offset:512
	global_load_dword v169, v[22:23], off
	v_lshl_add_u64 v[22:23], s[2:3], 0, v[20:21]
	global_load_dword v170, v[22:23], off offset:512
	global_load_dword v171, v[22:23], off
	v_add_u32_e32 v22, 0x2100, v34
	v_ashrrev_i32_e32 v23, 31, v22
	v_lshlrev_b64 v[22:23], 2, v[22:23]
	v_lshl_add_u64 v[26:27], s[20:21], 0, v[22:23]
	v_lshl_add_u64 v[22:23], s[2:3], 0, v[22:23]
	global_load_dword v172, v[26:27], off offset:512
	global_load_dword v173, v[26:27], off
	global_load_dword v174, v[22:23], off offset:512
	global_load_dword v175, v[22:23], off
	v_add_u32_e32 v22, 0x2200, v34
	v_ashrrev_i32_e32 v23, 31, v22
	v_lshlrev_b64 v[22:23], 2, v[22:23]
	v_lshl_add_u64 v[26:27], s[20:21], 0, v[22:23]
	global_load_dword v176, v[26:27], off offset:512
	global_load_dword v177, v[26:27], off
	v_lshl_add_u64 v[26:27], s[2:3], 0, v[22:23]
	global_load_dword v178, v[26:27], off offset:512
	global_load_dword v179, v[26:27], off
	v_add_u32_e32 v26, 0x2300, v34
	v_ashrrev_i32_e32 v27, 31, v26
	v_lshlrev_b64 v[28:29], 2, v[26:27]
	v_lshl_add_u64 v[30:31], s[20:21], 0, v[28:29]
	v_lshl_add_u64 v[28:29], s[2:3], 0, v[28:29]
	global_load_dword v180, v[30:31], off offset:512
	global_load_dword v181, v[30:31], off
	global_load_dword v182, v[28:29], off offset:512
	global_load_dword v183, v[28:29], off
	v_add_u32_e32 v28, 0x3000, v34
	v_ashrrev_i32_e32 v29, 31, v28
	v_lshlrev_b64 v[28:29], 2, v[28:29]
	v_lshl_add_u64 v[30:31], s[20:21], 0, v[28:29]
	global_load_dword v184, v[30:31], off offset:512
	global_load_dword v185, v[30:31], off
	v_lshl_add_u64 v[30:31], s[2:3], 0, v[28:29]
	global_load_dword v186, v[30:31], off offset:512
	global_load_dword v187, v[30:31], off
	v_add_u32_e32 v30, 0x3100, v34
	v_ashrrev_i32_e32 v31, 31, v30
	v_lshlrev_b64 v[30:31], 2, v[30:31]
	v_lshl_add_u64 v[36:37], s[20:21], 0, v[30:31]
	v_lshl_add_u64 v[30:31], s[2:3], 0, v[30:31]
	global_load_dword v188, v[36:37], off offset:512
	global_load_dword v189, v[36:37], off
	global_load_dword v190, v[30:31], off offset:512
	global_load_dword v191, v[30:31], off
	v_add_u32_e32 v30, 0x3200, v34
	v_ashrrev_i32_e32 v31, 31, v30
	v_lshlrev_b64 v[30:31], 2, v[30:31]
	v_lshl_add_u64 v[36:37], s[20:21], 0, v[30:31]
	v_add_u32_e32 v34, 0x3300, v34
	global_load_dword v192, v[36:37], off offset:512
	global_load_dword v193, v[36:37], off
	v_lshl_add_u64 v[36:37], s[2:3], 0, v[30:31]
	global_load_dword v194, v[36:37], off offset:512
	global_load_dword v195, v[36:37], off
	v_ashrrev_i32_e32 v35, 31, v34
	v_lshlrev_b64 v[36:37], 2, v[34:35]
	v_lshl_add_u64 v[38:39], s[20:21], 0, v[36:37]
	v_lshl_add_u64 v[36:37], s[2:3], 0, v[36:37]
	global_load_dword v196, v[38:39], off offset:512
	global_load_dword v197, v[38:39], off
	v_lshl_add_u64 v[38:39], s[0:1], 0, v[2:3]
	s_mov_b64 s[0:1], 0x1000
	v_mul_u32_u24_e32 v3, 0x440, v86
	global_load_dword v210, v[36:37], off offset:512
	global_load_dword v211, v[36:37], off
	v_lshlrev_b32_e32 v36, 3, v1
	v_and_b32_e32 v60, 0x78, v36
	v_lshlrev_b32_e32 v56, 2, v60
	v_lshl_add_u64 v[36:37], s[80:81], 0, v[56:57]
	v_lshl_add_u64 v[48:49], v[36:37], 0, s[0:1]
	s_movk_i32 s0, 0x2000
	v_add_co_u32_e64 v44, s[40:41], s0, v36
	s_mov_b64 s[0:1], 0x2000
	v_lshl_add_u64 v[50:51], v[36:37], 0, s[0:1]
	s_mov_b64 s[0:1], 0x3000
	v_addc_co_u32_e64 v45, s[40:41], 0, v37, s[40:41]
	v_lshl_add_u64 v[52:53], v[36:37], 0, s[0:1]
	s_movk_i32 s0, 0x3000
	v_add_co_u32_e64 v54, s[40:41], s0, v36
	s_movk_i32 s0, 0x100
	s_nop 0
	v_addc_co_u32_e64 v55, s[40:41], 0, v37, s[40:41]
	v_lshlrev_b64 v[36:37], 2, v[38:39]
	v_lshl_add_u64 v[38:39], s[52:53], 0, v[36:37]
	v_lshl_add_u64 v[40:41], s[56:57], 0, v[36:37]
	v_lshl_add_u64 v[36:37], s[58:59], 0, v[36:37]
	v_cmp_lt_i32_e64 s[40:41], s83, v1
	v_cmp_gt_i32_e64 s[42:43], s0, v1
	v_lshlrev_b32_e32 v120, 1, v60
	s_waitcnt vmcnt(0)
	v_cvt_pk_bf16_f32 v20, v169, v168
	v_cvt_pk_bf16_f32 v24, v171, v170
	v_cvt_pk_bf16_f32 v21, v173, v172
	v_cvt_pk_bf16_f32 v25, v175, v174
	v_cvt_pk_bf16_f32 v22, v177, v176
	v_cvt_pk_bf16_f32 v26, v179, v178
	v_cvt_pk_bf16_f32 v23, v181, v180
	v_cvt_pk_bf16_f32 v27, v183, v182
	v_cvt_pk_bf16_f32 v28, v185, v184
	v_cvt_pk_bf16_f32 v32, v187, v186
	v_cvt_pk_bf16_f32 v29, v189, v188
	v_cvt_pk_bf16_f32 v33, v191, v190
	v_cvt_pk_bf16_f32 v30, v193, v192
	v_cvt_pk_bf16_f32 v34, v195, v194
	v_cvt_pk_bf16_f32 v31, v197, v196
	v_cvt_pk_bf16_f32 v35, v211, v210
	global_load_dword v122, v[38:39], off
	global_load_dword v123, v[40:41], off
	global_load_dword v125, v[36:37], off
	s_nop 0
	global_load_dwordx4 v[36:39], v56, s[80:81]
	global_load_dwordx4 v[40:43], v56, s[80:81] offset:16
	global_load_dwordx4 v[88:91], v[44:45], off offset:-4096
	s_nop 0
	global_load_dwordx4 v[44:47], v[44:45], off
	s_nop 0
	global_load_dwordx4 v[92:95], v[48:49], off offset:16
	s_nop 0
	global_load_dwordx4 v[48:51], v[50:51], off offset:16
	s_nop 0
	global_load_dwordx4 v[100:103], v[54:55], off
	global_load_dwordx4 v[96:99], v[52:53], off offset:16
	s_nop 0
	global_load_dwordx4 v[52:55], v56, s[48:49]
	s_nop 0
	global_load_dwordx4 v[56:59], v56, s[48:49] offset:16
	s_waitcnt lgkmcnt(0)
	s_barrier
	s_and_saveexec_b64 s[0:1], s[42:43]
	s_xor_b64 s[0:1], exec, s[0:1]
	s_cbranch_execz .LBB0_281
	v_lshlrev_b32_e32 v127, 1, v60
	v_mul_u32_u24_e32 v3, 0x440, v86
	s_waitcnt vmcnt(4)
	v_mov_b32_e32 v118, v50
	s_waitcnt vmcnt(2)
	v_mov_b32_e32 v119, v98
	v_mov_b32_e32 v50, v99
	v_mov_b32_e32 v110, v42
	v_mov_b32_e32 v111, v94
	v_mov_b32_e32 v42, v95
	v_mov_b32_e32 v116, v48
	v_mov_b32_e32 v117, v96
	v_mov_b32_e32 v48, v97
	v_mov_b32_e32 v108, v40
	v_mov_b32_e32 v109, v92
	v_mov_b32_e32 v40, v93
	v_mov_b32_e32 v114, v46
	v_mov_b32_e32 v115, v102
	v_mov_b32_e32 v46, v103
	v_mov_b32_e32 v106, v38
	v_mov_b32_e32 v107, v90
	v_mov_b32_e32 v38, v91
	v_mov_b32_e32 v112, v44
	v_mov_b32_e32 v113, v100
	v_mov_b32_e32 v44, v101
	v_mov_b32_e32 v104, v36
	v_mov_b32_e32 v105, v88
	v_mov_b32_e32 v36, v89
